# index-query tile prefetch moved one chunk earlier (issued in the last latent-chunk iteration), head weights at the tail start
# baseline (speedup 1.0000x reference)
; #define TILE_LOAD(SLOT, CC, TT) do { const bf16_t* kp = P.KI + (rowb + 64 * (CC) + 16 * (TT) + r16) * 64 + 8 * g; Bk[SLOT][0] = *(const bf16x8*)kp; Bk[SLOT][1] = *(const bf16x8*)(kp + 32); } while (0)
; __device__ __forceinline__ void attn_item(const Ptrs& P, unsigned char* lds, int b, int tq0, int tid) {
;     ...
;         for (int q = 0; q < 4; ++q) { const bf16_t* qp = P.QI + (rowb + tq0 + q) * 1024 + r16 * 64 + 8 * g; Aq[q][0] = *(const bf16x8*)qp; Aq[q][1] = *(const bf16x8*)(qp + 32);
;             wq[q] = *(const f32x4*)(P.WI + (rowb + tq0 + q) * 16 + 4 * g); }
;         unsigned* KB = (unsigned*)lds;
;         const int nch = (tmax >> 6) + 1;
;         const int ni = (w < nch) ? ((nch - w + 7) >> 3) : 0;
;         bf16x8 Bk[4][2];
;     ...
;         if (ni > 0) { TILE_LOAD(0, w, 0); TILE_LOAD(1, w, 1); }
.Lpf_last:
	v_mov_b32_e32 v52, 0x24108
	ds_read_b32 v52, v52
	s_mov_b32 s96, 0
	s_waitcnt lgkmcnt(0)
	v_readfirstlane_b32 s90, v52
	s_nop 3
	s_cmp_gt_u32 s90, 0x7ff
	s_cbranch_scc1 .LBB0_926
	s_lshl_b32 s90, s90, 2
	s_sub_u32 s90, 0x1ffc, s90
	s_cmp_lt_u32 s90, 0xfd
	s_cbranch_scc1 .LBB0_926
	s_add_u32 s90, s90, s81
	s_mov_b32 s95, 0
	s_lshl_b32 s94, s90, 11
	v_lshl_add_u64 v[52:53], v[168:169], 0, s[94:95]
	s_add_u32 s94, s94, 0x1000
	v_lshl_add_u64 v[54:55], v[168:169], 0, s[94:95]
	global_load_dwordx4 v[88:91], v[52:53], off
	global_load_dwordx4 v[92:95], v[52:53], off offset:64
	global_load_dwordx4 v[116:119], v[52:53], off offset:2048
	global_load_dwordx4 v[120:123], v[52:53], off offset:2112
	global_load_dwordx4 v[132:135], v[54:55], off
	global_load_dwordx4 v[140:143], v[54:55], off offset:64
	global_load_dwordx4 v[144:147], v[54:55], off offset:2048
	global_load_dwordx4 v[156:159], v[54:55], off offset:2112
	s_mov_b32 s96, 1
	s_branch .LBB0_926
	s_nop 0
	s_nop 0
	s_nop 0
	s_nop 0
.Lpro_pf:
	s_and_b32 s14, s63, 0xffffffc0
	v_add_u32_e32 v164, s81, v124
	s_ashr_i32 s15, s14, 31
	v_lshl_add_u64 v[48:49], s[14:15], 0, v[182:183]
	v_lshlrev_b64 v[48:49], 7, v[48:49]
	v_lshl_add_u64 v[60:61], v[172:173], 0, v[48:49]
	v_lshrrev_b32_e32 v127, 3, v65
	v_sub_u32_e32 v128, 0x1ffd, v64
	v_sub_u32_e32 v129, 0x1ffe, v64
	v_mov_b64_e32 v[150:151], v[60:61]
	s_mov_b64 s[18:19], 0x1000
	v_lshl_add_u64 v[152:153], v[60:61], 0, s[18:19]
	global_load_dwordx4 v[48:51], v[150:151], off
	global_load_dwordx4 v[52:55], v[150:151], off offset:1024
	global_load_dwordx4 v[56:59], v[150:151], off offset:2048
	global_load_dwordx4 v[60:63], v[150:151], off offset:3072
	global_load_dwordx4 v[64:67], v[152:153], off
	global_load_dwordx4 v[68:71], v[152:153], off offset:1024
	global_load_dwordx4 v[72:75], v[152:153], off offset:2048
	global_load_dwordx4 v[76:79], v[152:153], off offset:3072
	s_mov_b64 s[18:19], 0x10000
	v_lshl_add_u64 v[150:151], v[150:151], 0, s[18:19]
	v_lshl_add_u64 v[152:153], v[152:153], 0, s[18:19]
	s_mov_b32 s20, 0
	v_lshl_add_u32 v130, s62, 8, v203
	v_add_u32_e32 v155, 0x10000, v130
	v_add_u32_e32 v154, s14, v179
	s_nop 0
	v_readfirstlane_b32 s14, v127
	s_waitcnt vmcnt(8)
	v_mov_b32_e32 v36, v20
	v_mov_b32_e32 v37, v21
	v_mov_b32_e32 v38, v22
	v_mov_b32_e32 v39, v23
	v_mov_b32_e32 v32, v24
	v_mov_b32_e32 v33, v25
	v_mov_b32_e32 v34, v26
	v_mov_b32_e32 v35, v27
	v_mov_b32_e32 v44, v248
	v_mov_b32_e32 v45, v249
	v_mov_b32_e32 v46, v250
	v_mov_b32_e32 v47, v251
	v_mov_b32_e32 v40, v160
	v_mov_b32_e32 v41, v161
	v_mov_b32_e32 v42, v162
	v_mov_b32_e32 v43, v163
	v_mov_b32_e32 v0, v88
	v_mov_b32_e32 v1, v89
	v_mov_b32_e32 v2, v90
	v_mov_b32_e32 v3, v91
	v_mov_b32_e32 v4, v92
	v_mov_b32_e32 v5, v93
	v_mov_b32_e32 v6, v94
	v_mov_b32_e32 v7, v95
	v_mov_b32_e32 v8, v116
	v_mov_b32_e32 v9, v117
	v_mov_b32_e32 v10, v118
	v_mov_b32_e32 v11, v119
	v_mov_b32_e32 v12, v120
	v_mov_b32_e32 v13, v121
	v_mov_b32_e32 v14, v122
	v_mov_b32_e32 v15, v123
	v_mov_b32_e32 v16, v132
	v_mov_b32_e32 v17, v133
	v_mov_b32_e32 v18, v134
	v_mov_b32_e32 v19, v135
	v_mov_b32_e32 v20, v140
	v_mov_b32_e32 v21, v141
	v_mov_b32_e32 v22, v142
	v_mov_b32_e32 v23, v143
	v_mov_b32_e32 v24, v144
	v_mov_b32_e32 v25, v145
	v_mov_b32_e32 v26, v146
	v_mov_b32_e32 v27, v147
	v_mov_b32_e32 v28, v156
	v_mov_b32_e32 v29, v157
	v_mov_b32_e32 v30, v158
	v_mov_b32_e32 v31, v159
	s_nop 3
	s_branch .Lidx_loop
	s_nop 0
	s_nop 0
	s_nop 0
	s_nop 0
	s_nop 0
	s_nop 0
	s_nop 0
	s_nop 0
	s_nop 0
	s_nop 0
	s_nop 0
	s_nop 0
	s_nop 0
	s_nop 0
	s_nop 0
	s_nop 0
	s_nop 0

; __device__ __forceinline__ void attn_item(const Ptrs& P, unsigned char* lds, int b, int tq0, int tid) {
;     ...
;     {
;         float* cmb = (float*)stw;
; #pragma unroll
;         for (int dt = 0; dt < 8; ++dt)
; #pragma unroll
;             for (int j = 0; j < 4; ++j) cmb[(dt * 4 + j) * 64 + lane] = half ? oacc[dt][j] : oacc[8 + dt][j];
; #pragma unroll
;         for (int j = 0; j < 4; ++j) { cmb[2048 + j * 64 + lane] = mrun[j]; cmb[2304 + j * 64 + lane] = lrun[j]; }
;         asm volatile("s_waitcnt lgkmcnt(0)" ::: "memory");
;         if (lane == 0) xa[48 + w] = aseq;
.LBB0_928:
	s_cmp_eq_u32 s96, 1
	s_cbranch_scc0 .Lpf_skip
	s_mov_b32 s95, 0
	s_lshl_b32 s94, s90, 6
	v_lshl_add_u64 v[30:31], v[170:171], 0, s[94:95]
	global_load_dwordx4 v[248:251], v[30:31], off
	global_load_dwordx4 v[160:163], v[30:31], off offset:64
	global_load_dwordx4 v[20:23], v[30:31], off offset:128
	global_load_dwordx4 v[24:27], v[30:31], off offset:192
.Lpf_skip:
	s_nop 0
	s_nop 0
	v_lshl_add_u32 v0, v179, 2, s12
	v_cmp_eq_u32_e64 s[12:13], 0, v219
	s_nop 1
	v_cndmask_b32_e64 v3, v109, v149, s[12:13]
	v_cndmask_b32_e64 v4, v108, v148, s[12:13]
	v_cndmask_b32_e64 v1, v111, v151, s[12:13]
	v_cndmask_b32_e64 v2, v110, v150, s[12:13]
	ds_write2st64_b32 v0, v4, v3 offset1:1
	ds_write2st64_b32 v0, v2, v1 offset0:2 offset1:3
	v_cndmask_b32_e64 v3, v101, v137, s[12:13]
	v_cndmask_b32_e64 v4, v100, v136, s[12:13]
	v_cndmask_b32_e64 v1, v103, v139, s[12:13]
	v_cndmask_b32_e64 v2, v102, v138, s[12:13]
	ds_write2st64_b32 v0, v4, v3 offset0:4 offset1:5
	ds_write2st64_b32 v0, v2, v1 offset0:6 offset1:7
	v_cndmask_b32_e64 v3, v85, v125, s[12:13]
	v_cndmask_b32_e64 v4, v84, v124, s[12:13]
	v_cndmask_b32_e64 v1, v87, v127, s[12:13]
	v_cndmask_b32_e64 v2, v86, v126, s[12:13]
	ds_write2st64_b32 v0, v4, v3 offset0:8 offset1:9
	ds_write2st64_b32 v0, v2, v1 offset0:10 offset1:11
	v_cndmask_b32_e64 v3, v69, v113, s[12:13]
	v_cndmask_b32_e64 v4, v68, v112, s[12:13]
	v_cndmask_b32_e64 v1, v71, v115, s[12:13]
	v_cndmask_b32_e64 v2, v70, v114, s[12:13]
	ds_write2st64_b32 v0, v4, v3 offset0:12 offset1:13
	ds_write2st64_b32 v0, v2, v1 offset0:14 offset1:15
	v_cndmask_b32_e64 v3, v49, v105, s[12:13]
	v_cndmask_b32_e64 v4, v48, v104, s[12:13]
	v_cndmask_b32_e64 v1, v51, v107, s[12:13]
	v_cndmask_b32_e64 v2, v50, v106, s[12:13]
	ds_write2st64_b32 v0, v4, v3 offset0:16 offset1:17
	ds_write2st64_b32 v0, v2, v1 offset0:18 offset1:19
	v_cndmask_b32_e64 v3, v41, v97, s[12:13]
	v_cndmask_b32_e64 v4, v40, v96, s[12:13]
	v_cndmask_b32_e64 v1, v43, v99, s[12:13]
	v_cndmask_b32_e64 v2, v42, v98, s[12:13]
	ds_write2st64_b32 v0, v4, v3 offset0:20 offset1:21
	ds_write2st64_b32 v0, v2, v1 offset0:22 offset1:23
	v_cndmask_b32_e64 v3, v37, v81, s[12:13]
	v_cndmask_b32_e64 v4, v36, v80, s[12:13]
	v_cndmask_b32_e64 v1, v39, v83, s[12:13]
	v_cndmask_b32_e64 v2, v38, v82, s[12:13]
	ds_write2st64_b32 v0, v4, v3 offset0:24 offset1:25
	ds_write2st64_b32 v0, v2, v1 offset0:26 offset1:27
	v_cndmask_b32_e64 v3, v33, v45, s[12:13]
	v_cndmask_b32_e64 v4, v32, v44, s[12:13]
	v_cndmask_b32_e64 v1, v35, v47, s[12:13]
	v_cndmask_b32_e64 v2, v34, v46, s[12:13]
	ds_write2st64_b32 v0, v4, v3 offset0:28 offset1:29
	ds_write2st64_b32 v0, v2, v1 offset0:30 offset1:31
	ds_write2st64_b32 v0, v164, v233 offset0:32 offset1:33
	ds_write2st64_b32 v0, v191, v190 offset0:36 offset1:37
	ds_write2st64_b32 v0, v234, v235 offset0:34 offset1:35
	ds_write2st64_b32 v0, v187, v186 offset0:38 offset1:39
	s_waitcnt lgkmcnt(0)
	s_and_saveexec_b64 s[14:15], s[4:5]
	s_cbranch_execz .LBB0_930
	s_addk_i32 s16, 0xc0
	v_mov_b32_e32 v0, s16
	v_mov_b32_e32 v1, s21
	ds_write_b32 v0, v218
	s_waitcnt lgkmcnt(0)
